# 144-job 256x128-tile GEMM variants: same XCD-compact job permutation
# speedup vs baseline: 1.0012x; 1.0012x over previous
.LBB0_126:
	s_and_b64 vcc, exec, s[2:3]
	s_mov_b64 s[0:1], -1
	s_cbranch_vccnz .LBB0_136
	s_cmpk_gt_i32 s74, 0x8f
	s_cbranch_scc1 .LBB0_135
	s_and_b32 s98, s74, 7
	s_mul_i32 s98, s98, 18
	s_lshr_b32 s99, s74, 3
	s_add_i32 s0, s98, s99
	s_branch .LBB0_130
